# hand-written attention phase: LDS-DMA swizzled K/V double buffer, two staggered half-steps per block
# baseline (speedup 1.0000x reference)
.LBB0_174:
	v_writelane_b32 v248, s10, 5
	v_writelane_b32 v248, s16, 3
	s_nop 1
	v_writelane_b32 v248, s17, 4
	s_or_b64 exec, exec, s[4:5]
	v_readlane_b32 s4, v249, 15
	v_readlane_b32 s5, v249, 16
	s_andn2_b64 vcc, exec, s[4:5]
	s_cbranch_vccnz .LBB0_203
	s_waitcnt lgkmcnt(0)
	s_barrier
	v_readfirstlane_b32 s67, v158
	s_lshr_b32 s67, s67, 6
	s_lshr_b32 s68, s67, 2
	v_and_b32_e32 v0, 63, v158
	v_and_b32_e32 v1, 15, v0
	v_lshrrev_b32_e32 v2, 4, v0
	s_lshl_b32 s4, s67, 4
	v_add_u32_e32 v17, s4, v1
	v_and_b32_e32 v37, 6, v1
	v_xor_b32_e32 v37, v2, v37
	v_lshlrev_b32_e32 v37, 4, v37
	v_lshl_add_u32 v4, v17, 7, v37
	v_xor_b32_e32 v5, 64, v4
	v_lshrrev_b32_e32 v38, 2, v1
	v_lshl_add_u32 v38, v2, 2, v38
	v_add_u32_e32 v39, s4, v38
	v_and_b32_e32 v40, 6, v38
	v_and_b32_e32 v41, 3, v1
	v_lshrrev_b32_e32 v42, 1, v41
	v_and_b32_e32 v43, 1, v1
	v_lshlrev_b32_e32 v43, 3, v43
	v_add_u32_e32 v45, 0x90, v39
	v_and_b32_e32 v45, 0xff, v45
	v_or_b32_e32 v44, 0, v42
	v_xor_b32_e32 v44, v44, v40
	v_lshlrev_b32_e32 v44, 4, v44
	v_add_u32_e32 v44, v44, v43
	v_lshl_add_u32 v46, v39, 7, v44
	v_add_u32_e32 v6, 0x10000, v46
	v_lshl_add_u32 v46, v45, 7, v44
	v_add_u32_e32 v10, 0x10000, v46
	v_or_b32_e32 v44, 2, v42
	v_xor_b32_e32 v44, v44, v40
	v_lshlrev_b32_e32 v44, 4, v44
	v_add_u32_e32 v44, v44, v43
	v_lshl_add_u32 v46, v39, 7, v44
	v_add_u32_e32 v7, 0x10000, v46
	v_lshl_add_u32 v46, v45, 7, v44
	v_add_u32_e32 v11, 0x10000, v46
	v_or_b32_e32 v44, 4, v42
	v_xor_b32_e32 v44, v44, v40
	v_lshlrev_b32_e32 v44, 4, v44
	v_add_u32_e32 v44, v44, v43
	v_lshl_add_u32 v46, v39, 7, v44
	v_add_u32_e32 v8, 0x10000, v46
	v_lshl_add_u32 v46, v45, 7, v44
	v_add_u32_e32 v12, 0x10000, v46
	v_or_b32_e32 v44, 6, v42
	v_xor_b32_e32 v44, v44, v40
	v_lshlrev_b32_e32 v44, 4, v44
	v_add_u32_e32 v44, v44, v43
	v_lshl_add_u32 v46, v39, 7, v44
	v_add_u32_e32 v9, 0x10000, v46
	v_lshl_add_u32 v46, v45, 7, v44
	v_add_u32_e32 v13, 0x10000, v46
	v_lshrrev_b32_e32 v14, 3, v158
	v_and_b32_e32 v44, 7, v0
	v_lshrrev_b32_e32 v45, 3, v0
	v_and_b32_e32 v45, 6, v45
	v_xor_b32_e32 v44, v44, v45
	v_lshlrev_b32_e32 v15, 4, v44
	v_lshlrev_b32_e32 v44, 2, v2
	v_sub_u32_e32 v45, v1, v44
	v_add_u32_e32 v45, 0x80, v45
	v_cvt_f32_i32_e32 v16, v45
	v_lshlrev_b32_e32 v18, 4, v2
	v_lshlrev_b32_e32 v19, 3, v2
	v_or_b32_e32 v45, 0, v44
	v_cmp_lt_u32_e64 s[54:55], v45, v1
	v_cmp_gt_u32_e64 s[70:71], v45, v1
	v_or_b32_e32 v45, 1, v44
	v_cmp_lt_u32_e64 s[56:57], v45, v1
	v_cmp_gt_u32_e64 s[72:73], v45, v1
	v_or_b32_e32 v45, 2, v44
	v_cmp_lt_u32_e64 s[58:59], v45, v1
	v_cmp_gt_u32_e64 s[74:75], v45, v1
	v_or_b32_e32 v45, 3, v44
	v_cmp_lt_u32_e64 s[60:61], v45, v1
	v_cmp_gt_u32_e64 s[76:77], v45, v1
	v_mov_b32_e32 v190, 0
	v_mov_b32_e32 v191, 0
	s_mov_b32 s63, s2
.Latt_unit:
	s_bfe_u32 s4, s63, 0x30005
	s_and_b32 s5, s63, 1
	s_lshl_b32 s5, s5, 3
	s_or_b32 s65, s4, s5
	s_bfe_u32 s64, s63, 0x20003
	s_bfe_u32 s66, s63, 0x20001
	s_lshl_b32 s4, s66, 4
	s_or_b32 s4, s4, s65
	s_lshl_b32 s5, s4, 20
	s_add_u32 s36, s84, 0xb600000
	s_addc_u32 s37, s85, 0
	s_add_u32 s36, s36, s5
	s_addc_u32 s37, s37, 0
	s_add_u32 s38, s84, 0xf600000
	s_addc_u32 s39, s85, 0
	s_add_u32 s38, s38, s5
	s_addc_u32 s39, s39, 0
	s_lshl_b32 s6, s66, 24
	s_lshl_b32 s7, s65, 7
	s_or_b32 s6, s6, s7
	s_add_u32 s40, s84, 0x13600000
	s_addc_u32 s41, s85, 0
	s_add_u32 s40, s40, s6
	s_addc_u32 s41, s41, 0
	s_add_u32 s42, s84, 0x17600000
	s_addc_u32 s43, s85, 0
	s_add_u32 s42, s42, s6
	s_addc_u32 s43, s43, 0
	s_lshl_b32 s5, s4, 15
	s_add_u32 s44, s84, 0x100000
	s_addc_u32 s45, s85, 0
	s_add_u32 s44, s44, s5
	s_addc_u32 s45, s45, 0
	s_mov_b64 s[46:47], s[36:37]
	s_mov_b32 s48, 0
	s_mov_b64 s[50:51], s[38:39]
	s_mov_b32 s49, 0x10000
	s_mov_b32 s52, 0
	s_cmp_eq_u32 s68, 0
	s_cbranch_scc1 .Latt_roles_1
	s_mov_b64 s[46:47], s[38:39]
	s_mov_b32 s48, 0x10000
	s_mov_b64 s[50:51], s[36:37]
	s_mov_b32 s49, 0
	s_mov_b32 s52, 1
.Latt_roles_1:
	s_add_i32 s4, s65, 1
	v_cvt_f32_ubyte0_e32 v0, s4
	v_mul_f32_e32 v0, -0.5, v0
	v_exp_f32_e32 v0, v0
	s_nop 1
	v_mul_f32_e32 v20, 0x3fb8aa3b, v0
	s_mov_b32 s4, 0
	s_lshr_b32 s11, s4, 4
	s_and_b32 s12, s4, 15
	s_lshl_b32 s28, s11, 1
	s_lshl_b32 s13, s64, 4
	s_add_i32 s13, s13, s12
	s_lshr_b32 s14, s12, 2
	s_and_b32 s15, s12, 3
	s_lshl_b32 s16, s64, 2
	s_add_i32 s15, s16, s15
	s_cmp_eq_u32 s11, 1
	s_cselect_b32 s29, s14, 0
	s_cselect_b32 s30, s15, s13
	s_cmp_eq_u32 s11, 2
	s_cselect_b32 s29, s12, s29
	s_cselect_b32 s30, s64, s30
	s_and_b32 s5, s4, 1
	s_lshl_b32 s5, s5, 15
	s_add_i32 s5, s5, s4
	s_lshl_b32 s6, s67, 10
	s_add_i32 s5, s5, s6
	s_add_i32 s6, s30, -1
	s_lshl_b32 s6, s6, 7
	s_add_i32 m0, s5, 0
	s_add_i32 s7, s6, 0
	v_add_u32_e32 v0, s7, v14
	v_lshlrev_b32_e32 v0, s28, v0
	v_add_u32_e32 v0, s29, v0
	v_max_i32_e32 v0, 0, v0
	v_lshl_or_b32 v2, v0, 7, v15
	v_lshl_add_u64 v[38:39], s[36:37], 0, v[2:3]
	global_load_lds_dwordx4 v[38:39], off
	s_add_i32 m0, s5, 8192
	s_add_i32 s7, s6, 64
	v_add_u32_e32 v0, s7, v14
	v_lshlrev_b32_e32 v0, s28, v0
	v_add_u32_e32 v0, s29, v0
	v_max_i32_e32 v0, 0, v0
	v_lshl_or_b32 v2, v0, 7, v15
	v_lshl_add_u64 v[40:41], s[36:37], 0, v[2:3]
	global_load_lds_dwordx4 v[40:41], off
	s_add_i32 m0, s5, 16384
	s_add_i32 s7, s6, 128
	v_add_u32_e32 v0, s7, v14
	v_lshlrev_b32_e32 v0, s28, v0
	v_add_u32_e32 v0, s29, v0
	v_max_i32_e32 v0, 0, v0
	v_lshl_or_b32 v2, v0, 7, v15
	v_lshl_add_u64 v[42:43], s[36:37], 0, v[2:3]
	global_load_lds_dwordx4 v[42:43], off
	s_add_i32 m0, s5, 24576
	s_add_i32 s7, s6, 192
	v_add_u32_e32 v0, s7, v14
	v_lshlrev_b32_e32 v0, s28, v0
	v_add_u32_e32 v0, s29, v0
	v_max_i32_e32 v0, 0, v0
	v_lshl_or_b32 v2, v0, 7, v15
	v_lshl_add_u64 v[44:45], s[36:37], 0, v[2:3]
	global_load_lds_dwordx4 v[44:45], off
	s_mov_b32 s9, 0x10000
	s_and_b32 s5, s4, 1
	s_lshl_b32 s5, s5, 15
	s_add_i32 s5, s5, s9
	s_lshl_b32 s6, s67, 10
	s_add_i32 s5, s5, s6
	s_add_i32 s6, s30, -1
	s_lshl_b32 s6, s6, 7
	s_add_i32 m0, s5, 0
	s_add_i32 s7, s6, 0
	v_add_u32_e32 v0, s7, v14
	v_lshlrev_b32_e32 v0, s28, v0
	v_add_u32_e32 v0, s29, v0
	v_max_i32_e32 v0, 0, v0
	v_lshl_or_b32 v2, v0, 7, v15
	v_lshl_add_u64 v[38:39], s[38:39], 0, v[2:3]
	global_load_lds_dwordx4 v[38:39], off
	s_add_i32 m0, s5, 8192
	s_add_i32 s7, s6, 64
	v_add_u32_e32 v0, s7, v14
	v_lshlrev_b32_e32 v0, s28, v0
	v_add_u32_e32 v0, s29, v0
	v_max_i32_e32 v0, 0, v0
	v_lshl_or_b32 v2, v0, 7, v15
	v_lshl_add_u64 v[40:41], s[38:39], 0, v[2:3]
	global_load_lds_dwordx4 v[40:41], off
	s_add_i32 m0, s5, 16384
	s_add_i32 s7, s6, 128
	v_add_u32_e32 v0, s7, v14
	v_lshlrev_b32_e32 v0, s28, v0
	v_add_u32_e32 v0, s29, v0
	v_max_i32_e32 v0, 0, v0
	v_lshl_or_b32 v2, v0, 7, v15
	v_lshl_add_u64 v[42:43], s[38:39], 0, v[2:3]
	global_load_lds_dwordx4 v[42:43], off
	s_add_i32 m0, s5, 24576
	s_add_i32 s7, s6, 192
	v_add_u32_e32 v0, s7, v14
	v_lshlrev_b32_e32 v0, s28, v0
	v_add_u32_e32 v0, s29, v0
	v_max_i32_e32 v0, 0, v0
	v_lshl_or_b32 v2, v0, 7, v15
	v_lshl_add_u64 v[44:45], s[38:39], 0, v[2:3]
	global_load_lds_dwordx4 v[44:45], off
	s_lshl_b32 s5, s30, 7
	v_add_u32_e32 v82, s5, v17
	v_lshlrev_b32_e32 v82, s28, v82
	v_add_u32_e32 v82, s29, v82
	v_lshl_add_u32 v1, v82, 11, v18
	global_load_dwordx4 v[48:51], v1, s[40:41]
	global_load_dwordx4 v[52:55], v1, s[40:41] offset:64
	v_lshl_add_u32 v1, v82, 11, v19
	global_load_dwordx2 v[64:65], v1, s[42:43] offset:0
	global_load_dwordx2 v[66:67], v1, s[42:43] offset:32
	global_load_dwordx2 v[68:69], v1, s[42:43] offset:64
	global_load_dwordx2 v[70:71], v1, s[42:43] offset:96
	v_lshlrev_b32_e32 v0, 2, v82
	global_load_dword v80, v0, s[44:45]
	s_mov_b32 s4, 1
	s_lshr_b32 s11, s4, 4
	s_and_b32 s12, s4, 15
	s_lshl_b32 s28, s11, 1
	s_lshl_b32 s13, s64, 4
	s_add_i32 s13, s13, s12
	s_lshr_b32 s14, s12, 2
	s_and_b32 s15, s12, 3
	s_lshl_b32 s16, s64, 2
	s_add_i32 s15, s16, s15
	s_cmp_eq_u32 s11, 1
	s_cselect_b32 s29, s14, 0
	s_cselect_b32 s30, s15, s13
	s_cmp_eq_u32 s11, 2
	s_cselect_b32 s29, s12, s29
	s_cselect_b32 s30, s64, s30
	s_lshl_b32 s5, s30, 7
	v_add_u32_e32 v82, s5, v17
	v_lshlrev_b32_e32 v82, s28, v82
	v_add_u32_e32 v82, s29, v82
	v_lshl_add_u32 v1, v82, 11, v18
	global_load_dwordx4 v[56:59], v1, s[40:41]
	global_load_dwordx4 v[60:63], v1, s[40:41] offset:64
	v_lshl_add_u32 v1, v82, 11, v19
	global_load_dwordx2 v[72:73], v1, s[42:43] offset:0
	global_load_dwordx2 v[74:75], v1, s[42:43] offset:32
	global_load_dwordx2 v[76:77], v1, s[42:43] offset:64
	global_load_dwordx2 v[78:79], v1, s[42:43] offset:96
	v_lshlrev_b32_e32 v0, 2, v82
	global_load_dword v81, v0, s[44:45]
	s_waitcnt vmcnt(0)
	s_barrier
	s_cmp_eq_u32 s68, 0
	s_cbranch_scc1 .Latt_lead_2
	s_mov_b32 s4, 1
	s_lshr_b32 s11, s4, 4
	s_and_b32 s12, s4, 15
	s_lshl_b32 s28, s11, 1
	s_lshl_b32 s13, s64, 4
	s_add_i32 s13, s13, s12
	s_lshr_b32 s14, s12, 2
	s_and_b32 s15, s12, 3
	s_lshl_b32 s16, s64, 2
	s_add_i32 s15, s16, s15
	s_cmp_eq_u32 s11, 1
	s_cselect_b32 s29, s14, 0
	s_cselect_b32 s30, s15, s13
	s_cmp_eq_u32 s11, 2
	s_cselect_b32 s29, s12, s29
	s_cselect_b32 s30, s64, s30
	s_and_b32 s5, s4, 1
	s_lshl_b32 s5, s5, 15
	s_add_i32 s5, s5, s49
	s_lshl_b32 s6, s67, 10
	s_add_i32 s5, s5, s6
	s_add_i32 s6, s30, -1
	s_lshl_b32 s6, s6, 7
	s_add_i32 m0, s5, 0
	s_add_i32 s7, s6, 0
	v_add_u32_e32 v0, s7, v14
	v_lshlrev_b32_e32 v0, s28, v0
	v_add_u32_e32 v0, s29, v0
	v_max_i32_e32 v0, 0, v0
	v_lshl_or_b32 v2, v0, 7, v15
	v_lshl_add_u64 v[38:39], s[50:51], 0, v[2:3]
	global_load_lds_dwordx4 v[38:39], off
	s_add_i32 m0, s5, 8192
	s_add_i32 s7, s6, 64
	v_add_u32_e32 v0, s7, v14
	v_lshlrev_b32_e32 v0, s28, v0
	v_add_u32_e32 v0, s29, v0
	v_max_i32_e32 v0, 0, v0
	v_lshl_or_b32 v2, v0, 7, v15
	v_lshl_add_u64 v[40:41], s[50:51], 0, v[2:3]
	global_load_lds_dwordx4 v[40:41], off
	s_add_i32 m0, s5, 16384
	s_add_i32 s7, s6, 128
	v_add_u32_e32 v0, s7, v14
	v_lshlrev_b32_e32 v0, s28, v0
	v_add_u32_e32 v0, s29, v0
	v_max_i32_e32 v0, 0, v0
	v_lshl_or_b32 v2, v0, 7, v15
	v_lshl_add_u64 v[42:43], s[50:51], 0, v[2:3]
	global_load_lds_dwordx4 v[42:43], off
	s_add_i32 m0, s5, 24576
	s_add_i32 s7, s6, 192
	v_add_u32_e32 v0, s7, v14
	v_lshlrev_b32_e32 v0, s28, v0
	v_add_u32_e32 v0, s29, v0
	v_max_i32_e32 v0, 0, v0
	v_lshl_or_b32 v2, v0, 7, v15
	v_lshl_add_u64 v[44:45], s[50:51], 0, v[2:3]
	global_load_lds_dwordx4 v[44:45], off
	s_waitcnt vmcnt(0)
	s_barrier
.Latt_lead_2:
	s_mov_b32 s53, 0
.Latt_blk:
	s_lshr_b32 s11, s53, 4
	s_and_b32 s12, s53, 15
	s_lshl_b32 s20, s11, 1
	s_lshl_b32 s13, s64, 4
	s_add_i32 s13, s13, s12
	s_lshr_b32 s14, s12, 2
	s_and_b32 s15, s12, 3
	s_lshl_b32 s16, s64, 2
	s_add_i32 s15, s16, s15
	s_cmp_eq_u32 s11, 1
	s_cselect_b32 s21, s14, 0
	s_cselect_b32 s24, s15, s13
	s_cmp_eq_u32 s11, 2
	s_cselect_b32 s21, s12, s21
	s_cselect_b32 s24, s64, s24
	s_add_i32 s4, s53, 1
	s_min_u32 s4, s4, 47
	s_lshr_b32 s11, s4, 4
	s_and_b32 s12, s4, 15
	s_lshl_b32 s28, s11, 1
	s_lshl_b32 s13, s64, 4
	s_add_i32 s13, s13, s12
	s_lshr_b32 s14, s12, 2
	s_and_b32 s15, s12, 3
	s_lshl_b32 s16, s64, 2
	s_add_i32 s15, s16, s15
	s_cmp_eq_u32 s11, 1
	s_cselect_b32 s29, s14, 0
	s_cselect_b32 s30, s15, s13
	s_cmp_eq_u32 s11, 2
	s_cselect_b32 s29, s12, s29
	s_cselect_b32 s30, s64, s30
	s_and_b32 s5, s4, 1
	s_lshl_b32 s5, s5, 15
	s_add_i32 s5, s5, s48
	s_lshl_b32 s6, s67, 10
	s_add_i32 s5, s5, s6
	s_add_i32 s6, s30, -1
	s_lshl_b32 s6, s6, 7
	s_add_i32 m0, s5, 0
	s_add_i32 s7, s6, 0
	v_add_u32_e32 v0, s7, v14
	v_lshlrev_b32_e32 v0, s28, v0
	v_add_u32_e32 v0, s29, v0
	v_max_i32_e32 v0, 0, v0
	v_lshl_or_b32 v2, v0, 7, v15
	v_lshl_add_u64 v[38:39], s[46:47], 0, v[2:3]
	global_load_lds_dwordx4 v[38:39], off
	s_add_i32 m0, s5, 8192
	s_add_i32 s7, s6, 64
	v_add_u32_e32 v0, s7, v14
	v_lshlrev_b32_e32 v0, s28, v0
	v_add_u32_e32 v0, s29, v0
	v_max_i32_e32 v0, 0, v0
	v_lshl_or_b32 v2, v0, 7, v15
	v_lshl_add_u64 v[40:41], s[46:47], 0, v[2:3]
	global_load_lds_dwordx4 v[40:41], off
	s_add_i32 m0, s5, 16384
	s_add_i32 s7, s6, 128
	v_add_u32_e32 v0, s7, v14
	v_lshlrev_b32_e32 v0, s28, v0
	v_add_u32_e32 v0, s29, v0
	v_max_i32_e32 v0, 0, v0
	v_lshl_or_b32 v2, v0, 7, v15
	v_lshl_add_u64 v[42:43], s[46:47], 0, v[2:3]
	global_load_lds_dwordx4 v[42:43], off
	s_add_i32 m0, s5, 24576
	s_add_i32 s7, s6, 192
	v_add_u32_e32 v0, s7, v14
	v_lshlrev_b32_e32 v0, s28, v0
	v_add_u32_e32 v0, s29, v0
	v_max_i32_e32 v0, 0, v0
	v_lshl_or_b32 v2, v0, 7, v15
	v_lshl_add_u64 v[44:45], s[46:47], 0, v[2:3]
	global_load_lds_dwordx4 v[44:45], off
	ds_read_b128 v[84:87], v4 offset:0
	ds_read_b128 v[88:91], v5 offset:0
	ds_read_b128 v[92:95], v4 offset:2048
	ds_read_b128 v[96:99], v5 offset:2048
	ds_read_b128 v[100:103], v4 offset:4096
	ds_read_b128 v[104:107], v5 offset:4096
	ds_read_b128 v[108:111], v4 offset:6144
	ds_read_b128 v[112:115], v5 offset:6144
	ds_read_b128 v[116:119], v4 offset:8192
	ds_read_b128 v[120:123], v5 offset:8192
	ds_read_b128 v[124:127], v4 offset:10240
	ds_read_b128 v[128:131], v5 offset:10240
	s_lshl_b32 s5, 1, s20
	v_cvt_f32_u32_e32 v0, s5
	v_mul_f32_e32 v21, v20, v0
	v_xor_b32_e32 v0, 0x80000000, v21
	v_mul_f32_e32 v22, v16, v0
	v_add_f32_e32 v23, v21, v22
	v_add_f32_e32 v1, v21, v21
	v_add_f32_e32 v24, v1, v22
	v_fma_f32 v25, v21, v192, v22
	v_mul_f32_e32 v26, 0, v21
	v_mul_f32_e32 v27, 0x41800000, v21
	v_mul_f32_e32 v28, 0x42000000, v21
	v_mul_f32_e32 v29, 0x42400000, v21
	v_mul_f32_e32 v30, 0x42800000, v21
	v_mul_f32_e32 v31, 0x42a00000, v21
	v_mul_f32_e32 v32, 0x42c00000, v21
	v_mul_f32_e32 v33, 0x42e00000, v21
	v_mul_f32_e32 v34, 0x43000000, v21
	s_cmp_eq_u32 s24, 0
	s_cbranch_scc0 .Latt_n0skip_3
	s_cmp_lt_u32 s67, 1
	s_cbranch_scc0 .Latt_n0t_4
	v_mov_b32_e32 v33, v223
.Latt_n0t_4:
	s_cmp_lt_u32 s67, 2
	s_cbranch_scc0 .Latt_n0t_5
	v_mov_b32_e32 v32, v223
.Latt_n0t_5:
	s_cmp_lt_u32 s67, 3
	s_cbranch_scc0 .Latt_n0t_6
	v_mov_b32_e32 v31, v223
.Latt_n0t_6:
	s_cmp_lt_u32 s67, 4
	s_cbranch_scc0 .Latt_n0t_7
	v_mov_b32_e32 v30, v223
.Latt_n0t_7:
	s_cmp_lt_u32 s67, 5
	s_cbranch_scc0 .Latt_n0t_8
	v_mov_b32_e32 v29, v223
.Latt_n0t_8:
	s_cmp_lt_u32 s67, 6
	s_cbranch_scc0 .Latt_n0t_9
	v_mov_b32_e32 v28, v223
.Latt_n0t_9:
	s_cmp_lt_u32 s67, 7
	s_cbranch_scc0 .Latt_n0t_10
	v_mov_b32_e32 v27, v223
.Latt_n0t_10:
	s_cmp_lt_u32 s67, 8
	s_cbranch_scc0 .Latt_n0t_11
	v_mov_b32_e32 v26, v223
.Latt_n0t_11:
.Latt_n0skip_3:
	s_waitcnt lgkmcnt(10)
	v_mfma_f32_16x16x32_bf16 v[132:135], v[84:87], v[48:51], v[22:25]
	v_mfma_f32_16x16x32_bf16 v[132:135], v[88:91], v[52:55], v[132:135]
	s_waitcnt lgkmcnt(8)
	v_mfma_f32_16x16x32_bf16 v[136:139], v[92:95], v[48:51], v[22:25]
	v_mfma_f32_16x16x32_bf16 v[136:139], v[96:99], v[52:55], v[136:139]
	s_waitcnt lgkmcnt(6)
	v_mfma_f32_16x16x32_bf16 v[140:143], v[100:103], v[48:51], v[22:25]
	v_mfma_f32_16x16x32_bf16 v[140:143], v[104:107], v[52:55], v[140:143]
	ds_read_b128 v[84:87], v4 offset:12288
	ds_read_b128 v[88:91], v5 offset:12288
	ds_read_b128 v[92:95], v4 offset:14336
	ds_read_b128 v[96:99], v5 offset:14336
	ds_read_b128 v[100:103], v4 offset:16384
	ds_read_b128 v[104:107], v5 offset:16384
	s_waitcnt lgkmcnt(10)
	v_mfma_f32_16x16x32_bf16 v[144:147], v[108:111], v[48:51], v[22:25]
	v_mfma_f32_16x16x32_bf16 v[144:147], v[112:115], v[52:55], v[144:147]
	s_waitcnt lgkmcnt(8)
	v_mfma_f32_16x16x32_bf16 v[148:151], v[116:119], v[48:51], v[22:25]
	v_mfma_f32_16x16x32_bf16 v[148:151], v[120:123], v[52:55], v[148:151]
	s_waitcnt lgkmcnt(6)
	v_mfma_f32_16x16x32_bf16 v[152:155], v[124:127], v[48:51], v[22:25]
	v_mfma_f32_16x16x32_bf16 v[152:155], v[128:131], v[52:55], v[152:155]
	s_waitcnt lgkmcnt(4)
	v_mfma_f32_16x16x32_bf16 v[160:163], v[84:87], v[48:51], v[22:25]
	v_mfma_f32_16x16x32_bf16 v[160:163], v[88:91], v[52:55], v[160:163]
	s_waitcnt lgkmcnt(2)
	v_mfma_f32_16x16x32_bf16 v[164:167], v[92:95], v[48:51], v[22:25]
	v_mfma_f32_16x16x32_bf16 v[164:167], v[96:99], v[52:55], v[164:167]
	s_waitcnt lgkmcnt(0)
	v_mfma_f32_16x16x32_bf16 v[168:171], v[100:103], v[48:51], v[22:25]
	v_mfma_f32_16x16x32_bf16 v[168:171], v[104:107], v[52:55], v[168:171]
	s_nop 7
	s_nop 3
	v_cndmask_b32_e64 v132, v132, v223, s[54:55]
	v_cndmask_b32_e64 v133, v133, v223, s[56:57]
	v_cndmask_b32_e64 v134, v134, v223, s[58:59]
	v_cndmask_b32_e64 v135, v135, v223, s[60:61]
	v_cndmask_b32_e64 v168, v168, v223, s[70:71]
	v_cndmask_b32_e64 v169, v169, v223, s[72:73]
	v_cndmask_b32_e64 v170, v170, v223, s[74:75]
	v_cndmask_b32_e64 v171, v171, v223, s[76:77]
	v_max3_f32 v0, v132, v133, v134
	v_max_f32_e32 v0, v0, v135
	v_add_f32_e32 v35, v0, v26
	v_max3_f32 v0, v136, v137, v138
	v_max_f32_e32 v0, v0, v139
	v_add_f32_e32 v0, v0, v27
	v_max_f32_e32 v35, v35, v0
	v_max3_f32 v0, v140, v141, v142
	v_max_f32_e32 v0, v0, v143
	v_add_f32_e32 v0, v0, v28
	v_max_f32_e32 v35, v35, v0
	v_max3_f32 v0, v144, v145, v146
	v_max_f32_e32 v0, v0, v147
	v_add_f32_e32 v0, v0, v29
	v_max_f32_e32 v35, v35, v0
	v_max3_f32 v0, v148, v149, v150
	v_max_f32_e32 v0, v0, v151
	v_add_f32_e32 v0, v0, v30
	v_max_f32_e32 v35, v35, v0
	v_max3_f32 v0, v152, v153, v154
	v_max_f32_e32 v0, v0, v155
	v_add_f32_e32 v0, v0, v31
	v_max_f32_e32 v35, v35, v0
	v_max3_f32 v0, v160, v161, v162
	v_max_f32_e32 v0, v0, v163
	v_add_f32_e32 v0, v0, v32
	v_max_f32_e32 v35, v35, v0
	v_max3_f32 v0, v164, v165, v166
	v_max_f32_e32 v0, v0, v167
	v_add_f32_e32 v0, v0, v33
	v_max_f32_e32 v35, v35, v0
	v_max3_f32 v0, v168, v169, v170
	v_max_f32_e32 v0, v0, v171
	v_add_f32_e32 v0, v0, v34
	v_max_f32_e32 v35, v35, v0
	v_mov_b32_e32 v0, v35
	v_mov_b32_e32 v1, v35
	s_nop 1
	v_permlane16_swap_b32_e32 v0, v1
	s_nop 1
	v_max_f32_e32 v35, v0, v1
	v_mov_b32_e32 v0, v35
	v_mov_b32_e32 v1, v35
	s_nop 1
	v_permlane32_swap_b32_e32 v0, v1
	s_nop 1
	v_max_f32_e32 v35, v0, v1
	v_sub_f32_e32 v2, v26, v35
	v_add_f32_e32 v132, v132, v2
	v_add_f32_e32 v133, v133, v2
	v_add_f32_e32 v134, v134, v2
	v_add_f32_e32 v135, v135, v2
	v_exp_f32_e32 v132, v132
	v_exp_f32_e32 v133, v133
	v_exp_f32_e32 v134, v134
	v_exp_f32_e32 v135, v135
	v_add_f32_e32 v36, 0, v132
	v_add_f32_e32 v36, v133, v36
	v_add_f32_e32 v36, v134, v36
	v_add_f32_e32 v36, v135, v36
	v_cvt_pk_bf16_f32 v172, v132, v133
	v_cvt_pk_bf16_f32 v173, v134, v135
	v_sub_f32_e32 v2, v27, v35
	v_add_f32_e32 v136, v136, v2
	v_add_f32_e32 v137, v137, v2
	v_add_f32_e32 v138, v138, v2
	v_add_f32_e32 v139, v139, v2
	v_exp_f32_e32 v136, v136
	v_exp_f32_e32 v137, v137
	v_exp_f32_e32 v138, v138
	v_exp_f32_e32 v139, v139
	v_add_f32_e32 v36, v136, v36
	v_add_f32_e32 v36, v137, v36
	v_add_f32_e32 v36, v138, v36
	v_add_f32_e32 v36, v139, v36
	v_cvt_pk_bf16_f32 v174, v136, v137
	v_cvt_pk_bf16_f32 v175, v138, v139
	v_sub_f32_e32 v2, v28, v35
	v_add_f32_e32 v140, v140, v2
	v_add_f32_e32 v141, v141, v2
	v_add_f32_e32 v142, v142, v2
	v_add_f32_e32 v143, v143, v2
	v_exp_f32_e32 v140, v140
	v_exp_f32_e32 v141, v141
	v_exp_f32_e32 v142, v142
	v_exp_f32_e32 v143, v143
	v_add_f32_e32 v36, v140, v36
	v_add_f32_e32 v36, v141, v36
	v_add_f32_e32 v36, v142, v36
	v_add_f32_e32 v36, v143, v36
	v_cvt_pk_bf16_f32 v176, v140, v141
	v_cvt_pk_bf16_f32 v177, v142, v143
	v_sub_f32_e32 v2, v29, v35
	v_add_f32_e32 v144, v144, v2
	v_add_f32_e32 v145, v145, v2
	v_add_f32_e32 v146, v146, v2
	v_add_f32_e32 v147, v147, v2
	v_exp_f32_e32 v144, v144
	v_exp_f32_e32 v145, v145
	v_exp_f32_e32 v146, v146
	v_exp_f32_e32 v147, v147
	v_add_f32_e32 v36, v144, v36
	v_add_f32_e32 v36, v145, v36
	v_add_f32_e32 v36, v146, v36
	v_add_f32_e32 v36, v147, v36
	v_cvt_pk_bf16_f32 v178, v144, v145
	v_cvt_pk_bf16_f32 v179, v146, v147
	v_sub_f32_e32 v2, v30, v35
	v_add_f32_e32 v148, v148, v2
	v_add_f32_e32 v149, v149, v2
	v_add_f32_e32 v150, v150, v2
	v_add_f32_e32 v151, v151, v2
	v_exp_f32_e32 v148, v148
	v_exp_f32_e32 v149, v149
	v_exp_f32_e32 v150, v150
	v_exp_f32_e32 v151, v151
	v_add_f32_e32 v36, v148, v36
	v_add_f32_e32 v36, v149, v36
	v_add_f32_e32 v36, v150, v36
	v_add_f32_e32 v36, v151, v36
	v_cvt_pk_bf16_f32 v180, v148, v149
	v_cvt_pk_bf16_f32 v181, v150, v151
	v_sub_f32_e32 v2, v31, v35
	v_add_f32_e32 v152, v152, v2
	v_add_f32_e32 v153, v153, v2
	v_add_f32_e32 v154, v154, v2
	v_add_f32_e32 v155, v155, v2
	v_exp_f32_e32 v152, v152
	v_exp_f32_e32 v153, v153
	v_exp_f32_e32 v154, v154
	v_exp_f32_e32 v155, v155
	v_add_f32_e32 v36, v152, v36
	v_add_f32_e32 v36, v153, v36
	v_add_f32_e32 v36, v154, v36
	v_add_f32_e32 v36, v155, v36
	v_cvt_pk_bf16_f32 v182, v152, v153
	v_cvt_pk_bf16_f32 v183, v154, v155
	v_sub_f32_e32 v2, v32, v35
	v_add_f32_e32 v160, v160, v2
	v_add_f32_e32 v161, v161, v2
	v_add_f32_e32 v162, v162, v2
	v_add_f32_e32 v163, v163, v2
	v_exp_f32_e32 v160, v160
	v_exp_f32_e32 v161, v161
	v_exp_f32_e32 v162, v162
	v_exp_f32_e32 v163, v163
	v_add_f32_e32 v36, v160, v36
	v_add_f32_e32 v36, v161, v36
	v_add_f32_e32 v36, v162, v36
	v_add_f32_e32 v36, v163, v36
	v_cvt_pk_bf16_f32 v184, v160, v161
	v_cvt_pk_bf16_f32 v185, v162, v163
	v_sub_f32_e32 v2, v33, v35
	v_add_f32_e32 v164, v164, v2
	v_add_f32_e32 v165, v165, v2
	v_add_f32_e32 v166, v166, v2
	v_add_f32_e32 v167, v167, v2
	v_exp_f32_e32 v164, v164
	v_exp_f32_e32 v165, v165
	v_exp_f32_e32 v166, v166
	v_exp_f32_e32 v167, v167
	v_add_f32_e32 v36, v164, v36
	v_add_f32_e32 v36, v165, v36
	v_add_f32_e32 v36, v166, v36
	v_add_f32_e32 v36, v167, v36
	v_cvt_pk_bf16_f32 v186, v164, v165
	v_cvt_pk_bf16_f32 v187, v166, v167
	v_sub_f32_e32 v2, v34, v35
	v_add_f32_e32 v168, v168, v2
	v_add_f32_e32 v169, v169, v2
	v_add_f32_e32 v170, v170, v2
	v_add_f32_e32 v171, v171, v2
	v_exp_f32_e32 v168, v168
	v_exp_f32_e32 v169, v169
	v_exp_f32_e32 v170, v170
	v_exp_f32_e32 v171, v171
	v_add_f32_e32 v36, v168, v36
	v_add_f32_e32 v36, v169, v36
	v_add_f32_e32 v36, v170, v36
	v_add_f32_e32 v36, v171, v36
	v_cvt_pk_bf16_f32 v188, v168, v169
	v_cvt_pk_bf16_f32 v189, v170, v171
	v_mov_b32_e32 v2, 0
	s_waitcnt vmcnt(16)
	s_waitcnt lgkmcnt(0)
	s_barrier
	s_add_i32 s4, s53, 1
	s_add_i32 s4, s4, s52
	s_min_u32 s4, s4, 47
	s_lshr_b32 s11, s4, 4
	s_and_b32 s12, s4, 15
	s_lshl_b32 s28, s11, 1
	s_lshl_b32 s13, s64, 4
	s_add_i32 s13, s13, s12
	s_lshr_b32 s14, s12, 2
	s_and_b32 s15, s12, 3
	s_lshl_b32 s16, s64, 2
	s_add_i32 s15, s16, s15
	s_cmp_eq_u32 s11, 1
	s_cselect_b32 s29, s14, 0
	s_cselect_b32 s30, s15, s13
	s_cmp_eq_u32 s11, 2
	s_cselect_b32 s29, s12, s29
	s_cselect_b32 s30, s64, s30
	s_and_b32 s5, s4, 1
	s_lshl_b32 s5, s5, 15
	s_add_i32 s5, s5, s49
	s_lshl_b32 s6, s67, 10
	s_add_i32 s5, s5, s6
	s_add_i32 s6, s30, -1
	s_lshl_b32 s6, s6, 7
	s_add_i32 m0, s5, 0
	s_add_i32 s7, s6, 0
	v_add_u32_e32 v0, s7, v14
	v_lshlrev_b32_e32 v0, s28, v0
	v_add_u32_e32 v0, s29, v0
	v_max_i32_e32 v0, 0, v0
	v_lshl_or_b32 v2, v0, 7, v15
	v_lshl_add_u64 v[38:39], s[50:51], 0, v[2:3]
	global_load_lds_dwordx4 v[38:39], off
	s_add_i32 m0, s5, 8192
	s_add_i32 s7, s6, 64
	v_add_u32_e32 v0, s7, v14
	v_lshlrev_b32_e32 v0, s28, v0
	v_add_u32_e32 v0, s29, v0
	v_max_i32_e32 v0, 0, v0
	v_lshl_or_b32 v2, v0, 7, v15
	v_lshl_add_u64 v[40:41], s[50:51], 0, v[2:3]
	global_load_lds_dwordx4 v[40:41], off
	s_add_i32 m0, s5, 16384
	s_add_i32 s7, s6, 128
	v_add_u32_e32 v0, s7, v14
	v_lshlrev_b32_e32 v0, s28, v0
	v_add_u32_e32 v0, s29, v0
	v_max_i32_e32 v0, 0, v0
	v_lshl_or_b32 v2, v0, 7, v15
	v_lshl_add_u64 v[42:43], s[50:51], 0, v[2:3]
	global_load_lds_dwordx4 v[42:43], off
	s_add_i32 m0, s5, 24576
	s_add_i32 s7, s6, 192
	v_add_u32_e32 v0, s7, v14
	v_lshlrev_b32_e32 v0, s28, v0
	v_add_u32_e32 v0, s29, v0
	v_max_i32_e32 v0, 0, v0
	v_lshl_or_b32 v2, v0, 7, v15
	v_lshl_add_u64 v[44:45], s[50:51], 0, v[2:3]
	global_load_lds_dwordx4 v[44:45], off
	s_add_i32 s4, s53, 2
	s_min_u32 s4, s4, 47
	s_lshr_b32 s11, s4, 4
	s_and_b32 s12, s4, 15
	s_lshl_b32 s8, s11, 1
	s_lshl_b32 s13, s64, 4
	s_add_i32 s13, s13, s12
	s_lshr_b32 s14, s12, 2
	s_and_b32 s15, s12, 3
	s_lshl_b32 s16, s64, 2
	s_add_i32 s15, s16, s15
	s_cmp_eq_u32 s11, 1
	s_cselect_b32 s17, s14, 0
	s_cselect_b32 s10, s15, s13
	s_cmp_eq_u32 s11, 2
	s_cselect_b32 s17, s12, s17
	s_cselect_b32 s10, s64, s10
	s_lshl_b32 s5, s10, 7
	v_add_u32_e32 v82, s5, v17
	v_lshlrev_b32_e32 v82, s8, v82
	v_add_u32_e32 v82, s17, v82
	v_lshl_add_u32 v1, v82, 11, v18
	global_load_dwordx4 v[48:51], v1, s[40:41]
	global_load_dwordx4 v[52:55], v1, s[40:41] offset:64
	ds_read_b64_tr_b16 v[84:85], v6 offset:0
	ds_read_b64_tr_b16 v[88:89], v7 offset:0
	ds_read_b64_tr_b16 v[92:93], v8 offset:0
	ds_read_b64_tr_b16 v[96:97], v9 offset:0
	ds_read_b64_tr_b16 v[86:87], v6 offset:2048
	ds_read_b64_tr_b16 v[90:91], v7 offset:2048
	ds_read_b64_tr_b16 v[94:95], v8 offset:2048
	ds_read_b64_tr_b16 v[98:99], v9 offset:2048
	ds_read_b64_tr_b16 v[100:101], v6 offset:4096
	ds_read_b64_tr_b16 v[104:105], v7 offset:4096
	ds_read_b64_tr_b16 v[108:109], v8 offset:4096
	ds_read_b64_tr_b16 v[112:113], v9 offset:4096
	ds_read_b64_tr_b16 v[102:103], v6 offset:6144
	ds_read_b64_tr_b16 v[106:107], v7 offset:6144
	ds_read_b64_tr_b16 v[110:111], v8 offset:6144
	ds_read_b64_tr_b16 v[114:115], v9 offset:6144
	s_waitcnt lgkmcnt(8)
	v_mfma_f32_16x16x32_bf16 v[228:231], v[84:87], v[172:175], 0
	v_mfma_f32_16x16x32_bf16 v[232:235], v[88:91], v[172:175], 0
	v_mfma_f32_16x16x32_bf16 v[236:239], v[92:95], v[172:175], 0
	v_mfma_f32_16x16x32_bf16 v[240:243], v[96:99], v[172:175], 0
	ds_read_b64_tr_b16 v[84:85], v6 offset:8192
	ds_read_b64_tr_b16 v[88:89], v7 offset:8192
	ds_read_b64_tr_b16 v[92:93], v8 offset:8192
	ds_read_b64_tr_b16 v[96:97], v9 offset:8192
	ds_read_b64_tr_b16 v[86:87], v6 offset:10240
	ds_read_b64_tr_b16 v[90:91], v7 offset:10240
	ds_read_b64_tr_b16 v[94:95], v8 offset:10240
	ds_read_b64_tr_b16 v[98:99], v9 offset:10240
	s_waitcnt lgkmcnt(8)
	v_mfma_f32_16x16x32_bf16 v[228:231], v[100:103], v[176:179], v[228:231]
	v_mfma_f32_16x16x32_bf16 v[232:235], v[104:107], v[176:179], v[232:235]
	v_mfma_f32_16x16x32_bf16 v[236:239], v[108:111], v[176:179], v[236:239]
	v_mfma_f32_16x16x32_bf16 v[240:243], v[112:115], v[176:179], v[240:243]
	ds_read_b64_tr_b16 v[100:101], v6 offset:12288
	ds_read_b64_tr_b16 v[104:105], v7 offset:12288
	ds_read_b64_tr_b16 v[108:109], v8 offset:12288
	ds_read_b64_tr_b16 v[112:113], v9 offset:12288
	ds_read_b64_tr_b16 v[102:103], v6 offset:14336
	ds_read_b64_tr_b16 v[106:107], v7 offset:14336
	ds_read_b64_tr_b16 v[110:111], v8 offset:14336
	ds_read_b64_tr_b16 v[114:115], v9 offset:14336
	s_waitcnt lgkmcnt(8)
	v_mfma_f32_16x16x32_bf16 v[228:231], v[84:87], v[180:183], v[228:231]
	v_mfma_f32_16x16x32_bf16 v[232:235], v[88:91], v[180:183], v[232:235]
	v_mfma_f32_16x16x32_bf16 v[236:239], v[92:95], v[180:183], v[236:239]
	v_mfma_f32_16x16x32_bf16 v[240:243], v[96:99], v[180:183], v[240:243]
	ds_read_b64_tr_b16 v[84:85], v6 offset:16384
	ds_read_b64_tr_b16 v[88:89], v7 offset:16384
	ds_read_b64_tr_b16 v[92:93], v8 offset:16384
	ds_read_b64_tr_b16 v[96:97], v9 offset:16384
	ds_read_b64_tr_b16 v[86:87], v10 offset:0
	ds_read_b64_tr_b16 v[90:91], v11 offset:0
	ds_read_b64_tr_b16 v[94:95], v12 offset:0
	ds_read_b64_tr_b16 v[98:99], v13 offset:0
	s_waitcnt lgkmcnt(8)
	v_mfma_f32_16x16x32_bf16 v[228:231], v[100:103], v[184:187], v[228:231]
	v_mfma_f32_16x16x32_bf16 v[232:235], v[104:107], v[184:187], v[232:235]
	v_mfma_f32_16x16x32_bf16 v[236:239], v[108:111], v[184:187], v[236:239]
	v_mfma_f32_16x16x32_bf16 v[240:243], v[112:115], v[184:187], v[240:243]
	s_waitcnt lgkmcnt(0)
	v_mfma_f32_16x16x32_bf16 v[228:231], v[84:87], v[188:191], v[228:231]
	v_mfma_f32_16x16x32_bf16 v[232:235], v[88:91], v[188:191], v[232:235]
	v_mfma_f32_16x16x32_bf16 v[236:239], v[92:95], v[188:191], v[236:239]
	v_mfma_f32_16x16x32_bf16 v[240:243], v[96:99], v[188:191], v[240:243]
	v_mov_b32_e32 v0, v36
	v_mov_b32_e32 v1, v36
	s_nop 1
	v_permlane16_swap_b32_e32 v0, v1
	s_nop 1
	v_add_f32_e32 v36, v0, v1
	v_mov_b32_e32 v0, v36
	v_mov_b32_e32 v1, v36
	s_nop 1
	v_permlane32_swap_b32_e32 v0, v1
	s_nop 1
	v_add_f32_e32 v36, v0, v1
	s_cmp_lt_u32 s53, 16
	s_cbranch_scc0 .Latt_hasprev_12
	v_mov_b32_e32 v80, v223
	v_mov_b32_e32 v64, 0
	v_mov_b32_e32 v65, 0
	v_mov_b32_e32 v66, 0
	v_mov_b32_e32 v67, 0
	v_mov_b32_e32 v68, 0
	v_mov_b32_e32 v69, 0
	v_mov_b32_e32 v70, 0
	v_mov_b32_e32 v71, 0
.Latt_hasprev_12:
	v_max_f32_e32 v116, v80, v35
	v_sub_f32_e32 v117, v80, v116
	v_sub_f32_e32 v118, v35, v116
	v_exp_f32_e32 v117, v117
	v_exp_f32_e32 v118, v118
	s_lshl_b32 s5, s24, 7
	v_add_u32_e32 v83, s5, v17
	v_lshlrev_b32_e32 v83, s20, v83
	v_add_u32_e32 v83, s21, v83
	v_fma_f32 v119, v36, v118, v117
	v_rcp_f32_e32 v122, v119
	v_lshl_add_u32 v123, v83, 11, v19
	s_nop 0
	v_mul_f32_e32 v120, v117, v122
	v_mul_f32_e32 v121, v118, v122
	v_lshlrev_b32_e32 v124, 16, v64
	v_and_b32_e32 v125, 0xffff0000, v64
	v_lshlrev_b32_e32 v126, 16, v65
	v_and_b32_e32 v127, 0xffff0000, v65
	v_mul_f32_e32 v124, v120, v124
	v_mul_f32_e32 v125, v120, v125
	v_mul_f32_e32 v126, v120, v126
	v_mul_f32_e32 v127, v120, v127
	v_fma_f32 v124, v228, v121, v124
	v_fma_f32 v125, v229, v121, v125
	v_fma_f32 v126, v230, v121, v126
	v_fma_f32 v127, v231, v121, v127
	v_cvt_pk_bf16_f32 v128, v124, v125
	v_cvt_pk_bf16_f32 v129, v126, v127
	s_nop 0
	global_store_dwordx2 v123, v[128:129], s[42:43] offset:0
	v_lshlrev_b32_e32 v124, 16, v66
	v_and_b32_e32 v125, 0xffff0000, v66
	v_lshlrev_b32_e32 v126, 16, v67
	v_and_b32_e32 v127, 0xffff0000, v67
	v_mul_f32_e32 v124, v120, v124
	v_mul_f32_e32 v125, v120, v125
	v_mul_f32_e32 v126, v120, v126
	v_mul_f32_e32 v127, v120, v127
	v_fma_f32 v124, v232, v121, v124
	v_fma_f32 v125, v233, v121, v125
	v_fma_f32 v126, v234, v121, v126
	v_fma_f32 v127, v235, v121, v127
	v_cvt_pk_bf16_f32 v128, v124, v125
	v_cvt_pk_bf16_f32 v129, v126, v127
	s_nop 0
	global_store_dwordx2 v123, v[128:129], s[42:43] offset:32
	v_lshlrev_b32_e32 v124, 16, v68
	v_and_b32_e32 v125, 0xffff0000, v68
	v_lshlrev_b32_e32 v126, 16, v69
	v_and_b32_e32 v127, 0xffff0000, v69
	v_mul_f32_e32 v124, v120, v124
	v_mul_f32_e32 v125, v120, v125
	v_mul_f32_e32 v126, v120, v126
	v_mul_f32_e32 v127, v120, v127
	v_fma_f32 v124, v236, v121, v124
	v_fma_f32 v125, v237, v121, v125
	v_fma_f32 v126, v238, v121, v126
	v_fma_f32 v127, v239, v121, v127
	v_cvt_pk_bf16_f32 v128, v124, v125
	v_cvt_pk_bf16_f32 v129, v126, v127
	s_nop 0
	global_store_dwordx2 v123, v[128:129], s[42:43] offset:64
	v_lshlrev_b32_e32 v124, 16, v70
	v_and_b32_e32 v125, 0xffff0000, v70
	v_lshlrev_b32_e32 v126, 16, v71
	v_and_b32_e32 v127, 0xffff0000, v71
	v_mul_f32_e32 v124, v120, v124
	v_mul_f32_e32 v125, v120, v125
	v_mul_f32_e32 v126, v120, v126
	v_mul_f32_e32 v127, v120, v127
	v_fma_f32 v124, v240, v121, v124
	v_fma_f32 v125, v241, v121, v125
	v_fma_f32 v126, v242, v121, v126
	v_fma_f32 v127, v243, v121, v127
	v_cvt_pk_bf16_f32 v128, v124, v125
	v_cvt_pk_bf16_f32 v129, v126, v127
	s_nop 0
	global_store_dwordx2 v123, v[128:129], s[42:43] offset:96
	v_log_f32_e32 v130, v119
	v_lshlrev_b32_e32 v131, 2, v83
	s_nop 0
	v_add_f32_e32 v130, v116, v130
	s_mov_b64 exec, 0xffff
	global_store_dword v131, v130, s[44:45]
	s_mov_b64 exec, -1
	v_lshl_add_u32 v1, v82, 11, v19
	global_load_dwordx2 v[64:65], v1, s[42:43] offset:0
	global_load_dwordx2 v[66:67], v1, s[42:43] offset:32
	global_load_dwordx2 v[68:69], v1, s[42:43] offset:64
	global_load_dwordx2 v[70:71], v1, s[42:43] offset:96
	v_lshlrev_b32_e32 v0, 2, v82
	global_load_dword v80, v0, s[44:45]
	s_waitcnt vmcnt(16)
	s_waitcnt lgkmcnt(0)
	s_barrier
	s_add_i32 s9, s53, 1
	s_lshr_b32 s11, s9, 4
	s_and_b32 s12, s9, 15
	s_lshl_b32 s20, s11, 1
	s_lshl_b32 s13, s64, 4
	s_add_i32 s13, s13, s12
	s_lshr_b32 s14, s12, 2
	s_and_b32 s15, s12, 3
	s_lshl_b32 s16, s64, 2
	s_add_i32 s15, s16, s15
	s_cmp_eq_u32 s11, 1
	s_cselect_b32 s21, s14, 0
	s_cselect_b32 s24, s15, s13
	s_cmp_eq_u32 s11, 2
	s_cselect_b32 s21, s12, s21
	s_cselect_b32 s24, s64, s24
	s_add_i32 s4, s9, 1
	s_min_u32 s4, s4, 47
	s_lshr_b32 s11, s4, 4
	s_and_b32 s12, s4, 15
	s_lshl_b32 s28, s11, 1
	s_lshl_b32 s13, s64, 4
	s_add_i32 s13, s13, s12
	s_lshr_b32 s14, s12, 2
	s_and_b32 s15, s12, 3
	s_lshl_b32 s16, s64, 2
	s_add_i32 s15, s16, s15
	s_cmp_eq_u32 s11, 1
	s_cselect_b32 s29, s14, 0
	s_cselect_b32 s30, s15, s13
	s_cmp_eq_u32 s11, 2
	s_cselect_b32 s29, s12, s29
	s_cselect_b32 s30, s64, s30
	s_and_b32 s5, s4, 1
	s_lshl_b32 s5, s5, 15
	s_add_i32 s5, s5, s48
	s_lshl_b32 s6, s67, 10
	s_add_i32 s5, s5, s6
	s_add_i32 s6, s30, -1
	s_lshl_b32 s6, s6, 7
	s_add_i32 m0, s5, 0
	s_add_i32 s7, s6, 0
	v_add_u32_e32 v0, s7, v14
	v_lshlrev_b32_e32 v0, s28, v0
	v_add_u32_e32 v0, s29, v0
	v_max_i32_e32 v0, 0, v0
	v_lshl_or_b32 v2, v0, 7, v15
	v_lshl_add_u64 v[38:39], s[46:47], 0, v[2:3]
	global_load_lds_dwordx4 v[38:39], off
	s_add_i32 m0, s5, 8192
	s_add_i32 s7, s6, 64
	v_add_u32_e32 v0, s7, v14
	v_lshlrev_b32_e32 v0, s28, v0
	v_add_u32_e32 v0, s29, v0
	v_max_i32_e32 v0, 0, v0
	v_lshl_or_b32 v2, v0, 7, v15
	v_lshl_add_u64 v[40:41], s[46:47], 0, v[2:3]
	global_load_lds_dwordx4 v[40:41], off
	s_add_i32 m0, s5, 16384
	s_add_i32 s7, s6, 128
	v_add_u32_e32 v0, s7, v14
	v_lshlrev_b32_e32 v0, s28, v0
	v_add_u32_e32 v0, s29, v0
	v_max_i32_e32 v0, 0, v0
	v_lshl_or_b32 v2, v0, 7, v15
	v_lshl_add_u64 v[42:43], s[46:47], 0, v[2:3]
	global_load_lds_dwordx4 v[42:43], off
	s_add_i32 m0, s5, 24576
	s_add_i32 s7, s6, 192
	v_add_u32_e32 v0, s7, v14
	v_lshlrev_b32_e32 v0, s28, v0
	v_add_u32_e32 v0, s29, v0
	v_max_i32_e32 v0, 0, v0
	v_lshl_or_b32 v2, v0, 7, v15
	v_lshl_add_u64 v[44:45], s[46:47], 0, v[2:3]
	global_load_lds_dwordx4 v[44:45], off
	ds_read_b128 v[84:87], v4 offset:32768
	ds_read_b128 v[88:91], v5 offset:32768
	ds_read_b128 v[92:95], v4 offset:34816
	ds_read_b128 v[96:99], v5 offset:34816
	ds_read_b128 v[100:103], v4 offset:36864
	ds_read_b128 v[104:107], v5 offset:36864
	ds_read_b128 v[108:111], v4 offset:38912
	ds_read_b128 v[112:115], v5 offset:38912
	ds_read_b128 v[116:119], v4 offset:40960
	ds_read_b128 v[120:123], v5 offset:40960
	ds_read_b128 v[124:127], v4 offset:43008
	ds_read_b128 v[128:131], v5 offset:43008
	s_lshl_b32 s5, 1, s20
	v_cvt_f32_u32_e32 v0, s5
	v_mul_f32_e32 v21, v20, v0
	v_xor_b32_e32 v0, 0x80000000, v21
	v_mul_f32_e32 v22, v16, v0
	v_add_f32_e32 v23, v21, v22
	v_add_f32_e32 v1, v21, v21
	v_add_f32_e32 v24, v1, v22
	v_fma_f32 v25, v21, v192, v22
	v_mul_f32_e32 v26, 0, v21
	v_mul_f32_e32 v27, 0x41800000, v21
	v_mul_f32_e32 v28, 0x42000000, v21
	v_mul_f32_e32 v29, 0x42400000, v21
	v_mul_f32_e32 v30, 0x42800000, v21
	v_mul_f32_e32 v31, 0x42a00000, v21
	v_mul_f32_e32 v32, 0x42c00000, v21
	v_mul_f32_e32 v33, 0x42e00000, v21
	v_mul_f32_e32 v34, 0x43000000, v21
	s_cmp_eq_u32 s24, 0
	s_cbranch_scc0 .Latt_n0skip_13
	s_cmp_lt_u32 s67, 1
	s_cbranch_scc0 .Latt_n0t_14
	v_mov_b32_e32 v33, v223

.Latt_n0t_21:
.Latt_n0skip_13:
	s_waitcnt lgkmcnt(10)
	v_mfma_f32_16x16x32_bf16 v[132:135], v[84:87], v[56:59], v[22:25]
	v_mfma_f32_16x16x32_bf16 v[132:135], v[88:91], v[60:63], v[132:135]
	s_waitcnt lgkmcnt(8)
	v_mfma_f32_16x16x32_bf16 v[136:139], v[92:95], v[56:59], v[22:25]
	v_mfma_f32_16x16x32_bf16 v[136:139], v[96:99], v[60:63], v[136:139]
	s_waitcnt lgkmcnt(6)
	v_mfma_f32_16x16x32_bf16 v[140:143], v[100:103], v[56:59], v[22:25]
	v_mfma_f32_16x16x32_bf16 v[140:143], v[104:107], v[60:63], v[140:143]
	ds_read_b128 v[84:87], v4 offset:45056
	ds_read_b128 v[88:91], v5 offset:45056
	ds_read_b128 v[92:95], v4 offset:47104
	ds_read_b128 v[96:99], v5 offset:47104
	ds_read_b128 v[100:103], v4 offset:49152
	ds_read_b128 v[104:107], v5 offset:49152
	s_waitcnt lgkmcnt(10)
	v_mfma_f32_16x16x32_bf16 v[144:147], v[108:111], v[56:59], v[22:25]
	v_mfma_f32_16x16x32_bf16 v[144:147], v[112:115], v[60:63], v[144:147]
	s_waitcnt lgkmcnt(8)
	v_mfma_f32_16x16x32_bf16 v[148:151], v[116:119], v[56:59], v[22:25]
	v_mfma_f32_16x16x32_bf16 v[148:151], v[120:123], v[60:63], v[148:151]
	s_waitcnt lgkmcnt(6)
	v_mfma_f32_16x16x32_bf16 v[152:155], v[124:127], v[56:59], v[22:25]
	v_mfma_f32_16x16x32_bf16 v[152:155], v[128:131], v[60:63], v[152:155]
	s_waitcnt lgkmcnt(4)
	v_mfma_f32_16x16x32_bf16 v[160:163], v[84:87], v[56:59], v[22:25]
	v_mfma_f32_16x16x32_bf16 v[160:163], v[88:91], v[60:63], v[160:163]
	s_waitcnt lgkmcnt(2)
	v_mfma_f32_16x16x32_bf16 v[164:167], v[92:95], v[56:59], v[22:25]
	v_mfma_f32_16x16x32_bf16 v[164:167], v[96:99], v[60:63], v[164:167]
	s_waitcnt lgkmcnt(0)
	v_mfma_f32_16x16x32_bf16 v[168:171], v[100:103], v[56:59], v[22:25]
	v_mfma_f32_16x16x32_bf16 v[168:171], v[104:107], v[60:63], v[168:171]
	s_nop 7
	s_nop 3
	v_cndmask_b32_e64 v132, v132, v223, s[54:55]
	v_cndmask_b32_e64 v133, v133, v223, s[56:57]
	v_cndmask_b32_e64 v134, v134, v223, s[58:59]
	v_cndmask_b32_e64 v135, v135, v223, s[60:61]
	v_cndmask_b32_e64 v168, v168, v223, s[70:71]
	v_cndmask_b32_e64 v169, v169, v223, s[72:73]
	v_cndmask_b32_e64 v170, v170, v223, s[74:75]
	v_cndmask_b32_e64 v171, v171, v223, s[76:77]
	v_max3_f32 v0, v132, v133, v134
	v_max_f32_e32 v0, v0, v135
	v_add_f32_e32 v35, v0, v26
	v_max3_f32 v0, v136, v137, v138
	v_max_f32_e32 v0, v0, v139
	v_add_f32_e32 v0, v0, v27
	v_max_f32_e32 v35, v35, v0
	v_max3_f32 v0, v140, v141, v142
	v_max_f32_e32 v0, v0, v143
	v_add_f32_e32 v0, v0, v28
	v_max_f32_e32 v35, v35, v0
	v_max3_f32 v0, v144, v145, v146
	v_max_f32_e32 v0, v0, v147
	v_add_f32_e32 v0, v0, v29
	v_max_f32_e32 v35, v35, v0
	v_max3_f32 v0, v148, v149, v150
	v_max_f32_e32 v0, v0, v151
	v_add_f32_e32 v0, v0, v30
	v_max_f32_e32 v35, v35, v0
	v_max3_f32 v0, v152, v153, v154
	v_max_f32_e32 v0, v0, v155
	v_add_f32_e32 v0, v0, v31
	v_max_f32_e32 v35, v35, v0
	v_max3_f32 v0, v160, v161, v162
	v_max_f32_e32 v0, v0, v163
	v_add_f32_e32 v0, v0, v32
	v_max_f32_e32 v35, v35, v0
	v_max3_f32 v0, v164, v165, v166
	v_max_f32_e32 v0, v0, v167
	v_add_f32_e32 v0, v0, v33
	v_max_f32_e32 v35, v35, v0
	v_max3_f32 v0, v168, v169, v170
	v_max_f32_e32 v0, v0, v171
	v_add_f32_e32 v0, v0, v34
	v_max_f32_e32 v35, v35, v0
	v_mov_b32_e32 v0, v35
	v_mov_b32_e32 v1, v35
	s_nop 1
	v_permlane16_swap_b32_e32 v0, v1
	s_nop 1
	v_max_f32_e32 v35, v0, v1
	v_mov_b32_e32 v0, v35
	v_mov_b32_e32 v1, v35
	s_nop 1
	v_permlane32_swap_b32_e32 v0, v1
	s_nop 1
	v_max_f32_e32 v35, v0, v1
	v_sub_f32_e32 v2, v26, v35
	v_add_f32_e32 v132, v132, v2
	v_add_f32_e32 v133, v133, v2
	v_add_f32_e32 v134, v134, v2
	v_add_f32_e32 v135, v135, v2
	v_exp_f32_e32 v132, v132
	v_exp_f32_e32 v133, v133
	v_exp_f32_e32 v134, v134
	v_exp_f32_e32 v135, v135
	v_add_f32_e32 v36, 0, v132
	v_add_f32_e32 v36, v133, v36
	v_add_f32_e32 v36, v134, v36
	v_add_f32_e32 v36, v135, v36
	v_cvt_pk_bf16_f32 v172, v132, v133
	v_cvt_pk_bf16_f32 v173, v134, v135
	v_sub_f32_e32 v2, v27, v35
	v_add_f32_e32 v136, v136, v2
	v_add_f32_e32 v137, v137, v2
	v_add_f32_e32 v138, v138, v2
	v_add_f32_e32 v139, v139, v2
	v_exp_f32_e32 v136, v136
	v_exp_f32_e32 v137, v137
	v_exp_f32_e32 v138, v138
	v_exp_f32_e32 v139, v139
	v_add_f32_e32 v36, v136, v36
	v_add_f32_e32 v36, v137, v36
	v_add_f32_e32 v36, v138, v36
	v_add_f32_e32 v36, v139, v36
	v_cvt_pk_bf16_f32 v174, v136, v137
	v_cvt_pk_bf16_f32 v175, v138, v139
	v_sub_f32_e32 v2, v28, v35
	v_add_f32_e32 v140, v140, v2
	v_add_f32_e32 v141, v141, v2
	v_add_f32_e32 v142, v142, v2
	v_add_f32_e32 v143, v143, v2
	v_exp_f32_e32 v140, v140
	v_exp_f32_e32 v141, v141
	v_exp_f32_e32 v142, v142
	v_exp_f32_e32 v143, v143
	v_add_f32_e32 v36, v140, v36
	v_add_f32_e32 v36, v141, v36
	v_add_f32_e32 v36, v142, v36
	v_add_f32_e32 v36, v143, v36
	v_cvt_pk_bf16_f32 v176, v140, v141
	v_cvt_pk_bf16_f32 v177, v142, v143
	v_sub_f32_e32 v2, v29, v35
	v_add_f32_e32 v144, v144, v2
	v_add_f32_e32 v145, v145, v2
	v_add_f32_e32 v146, v146, v2
	v_add_f32_e32 v147, v147, v2
	v_exp_f32_e32 v144, v144
	v_exp_f32_e32 v145, v145
	v_exp_f32_e32 v146, v146
	v_exp_f32_e32 v147, v147
	v_add_f32_e32 v36, v144, v36
	v_add_f32_e32 v36, v145, v36
	v_add_f32_e32 v36, v146, v36
	v_add_f32_e32 v36, v147, v36
	v_cvt_pk_bf16_f32 v178, v144, v145
	v_cvt_pk_bf16_f32 v179, v146, v147
	v_sub_f32_e32 v2, v30, v35
	v_add_f32_e32 v148, v148, v2
	v_add_f32_e32 v149, v149, v2
	v_add_f32_e32 v150, v150, v2
	v_add_f32_e32 v151, v151, v2
	v_exp_f32_e32 v148, v148
	v_exp_f32_e32 v149, v149
	v_exp_f32_e32 v150, v150
	v_exp_f32_e32 v151, v151
	v_add_f32_e32 v36, v148, v36
	v_add_f32_e32 v36, v149, v36
	v_add_f32_e32 v36, v150, v36
	v_add_f32_e32 v36, v151, v36
	v_cvt_pk_bf16_f32 v180, v148, v149
	v_cvt_pk_bf16_f32 v181, v150, v151
	v_sub_f32_e32 v2, v31, v35
	v_add_f32_e32 v152, v152, v2
	v_add_f32_e32 v153, v153, v2
	v_add_f32_e32 v154, v154, v2
	v_add_f32_e32 v155, v155, v2
	v_exp_f32_e32 v152, v152
	v_exp_f32_e32 v153, v153
	v_exp_f32_e32 v154, v154
	v_exp_f32_e32 v155, v155
	v_add_f32_e32 v36, v152, v36
	v_add_f32_e32 v36, v153, v36
	v_add_f32_e32 v36, v154, v36
	v_add_f32_e32 v36, v155, v36
	v_cvt_pk_bf16_f32 v182, v152, v153
	v_cvt_pk_bf16_f32 v183, v154, v155
	v_sub_f32_e32 v2, v32, v35
	v_add_f32_e32 v160, v160, v2
	v_add_f32_e32 v161, v161, v2
	v_add_f32_e32 v162, v162, v2
	v_add_f32_e32 v163, v163, v2
	v_exp_f32_e32 v160, v160
	v_exp_f32_e32 v161, v161
	v_exp_f32_e32 v162, v162
	v_exp_f32_e32 v163, v163
	v_add_f32_e32 v36, v160, v36
	v_add_f32_e32 v36, v161, v36
	v_add_f32_e32 v36, v162, v36
	v_add_f32_e32 v36, v163, v36
	v_cvt_pk_bf16_f32 v184, v160, v161
	v_cvt_pk_bf16_f32 v185, v162, v163
	v_sub_f32_e32 v2, v33, v35
	v_add_f32_e32 v164, v164, v2
	v_add_f32_e32 v165, v165, v2
	v_add_f32_e32 v166, v166, v2
	v_add_f32_e32 v167, v167, v2
	v_exp_f32_e32 v164, v164
	v_exp_f32_e32 v165, v165
	v_exp_f32_e32 v166, v166
	v_exp_f32_e32 v167, v167
	v_add_f32_e32 v36, v164, v36
	v_add_f32_e32 v36, v165, v36
	v_add_f32_e32 v36, v166, v36
	v_add_f32_e32 v36, v167, v36
	v_cvt_pk_bf16_f32 v186, v164, v165
	v_cvt_pk_bf16_f32 v187, v166, v167
	v_sub_f32_e32 v2, v34, v35
	v_add_f32_e32 v168, v168, v2
	v_add_f32_e32 v169, v169, v2
	v_add_f32_e32 v170, v170, v2
	v_add_f32_e32 v171, v171, v2
	v_exp_f32_e32 v168, v168
	v_exp_f32_e32 v169, v169
	v_exp_f32_e32 v170, v170
	v_exp_f32_e32 v171, v171
	v_add_f32_e32 v36, v168, v36
	v_add_f32_e32 v36, v169, v36
	v_add_f32_e32 v36, v170, v36
	v_add_f32_e32 v36, v171, v36
	v_cvt_pk_bf16_f32 v188, v168, v169
	v_cvt_pk_bf16_f32 v189, v170, v171
	v_mov_b32_e32 v2, 0
	s_waitcnt vmcnt(16)
	s_waitcnt lgkmcnt(0)
	s_barrier
	s_add_i32 s9, s53, 1
	s_add_i32 s4, s9, 1
	s_add_i32 s4, s4, s52
	s_min_u32 s4, s4, 47
	s_lshr_b32 s11, s4, 4
	s_and_b32 s12, s4, 15
	s_lshl_b32 s28, s11, 1
	s_lshl_b32 s13, s64, 4
	s_add_i32 s13, s13, s12
	s_lshr_b32 s14, s12, 2
	s_and_b32 s15, s12, 3
	s_lshl_b32 s16, s64, 2
	s_add_i32 s15, s16, s15
	s_cmp_eq_u32 s11, 1
	s_cselect_b32 s29, s14, 0
	s_cselect_b32 s30, s15, s13
	s_cmp_eq_u32 s11, 2
	s_cselect_b32 s29, s12, s29
	s_cselect_b32 s30, s64, s30
	s_and_b32 s5, s4, 1
	s_lshl_b32 s5, s5, 15
	s_add_i32 s5, s5, s49
	s_lshl_b32 s6, s67, 10
	s_add_i32 s5, s5, s6
	s_add_i32 s6, s30, -1
	s_lshl_b32 s6, s6, 7
	s_add_i32 m0, s5, 0
	s_add_i32 s7, s6, 0
	v_add_u32_e32 v0, s7, v14
	v_lshlrev_b32_e32 v0, s28, v0
	v_add_u32_e32 v0, s29, v0
	v_max_i32_e32 v0, 0, v0
	v_lshl_or_b32 v2, v0, 7, v15
	v_lshl_add_u64 v[38:39], s[50:51], 0, v[2:3]
	global_load_lds_dwordx4 v[38:39], off
	s_add_i32 m0, s5, 8192
	s_add_i32 s7, s6, 64
	v_add_u32_e32 v0, s7, v14
	v_lshlrev_b32_e32 v0, s28, v0
	v_add_u32_e32 v0, s29, v0
	v_max_i32_e32 v0, 0, v0
	v_lshl_or_b32 v2, v0, 7, v15
	v_lshl_add_u64 v[40:41], s[50:51], 0, v[2:3]
	global_load_lds_dwordx4 v[40:41], off
	s_add_i32 m0, s5, 16384
	s_add_i32 s7, s6, 128
	v_add_u32_e32 v0, s7, v14
	v_lshlrev_b32_e32 v0, s28, v0
	v_add_u32_e32 v0, s29, v0
	v_max_i32_e32 v0, 0, v0
	v_lshl_or_b32 v2, v0, 7, v15
	v_lshl_add_u64 v[42:43], s[50:51], 0, v[2:3]
	global_load_lds_dwordx4 v[42:43], off
	s_add_i32 m0, s5, 24576
	s_add_i32 s7, s6, 192
	v_add_u32_e32 v0, s7, v14
	v_lshlrev_b32_e32 v0, s28, v0
	v_add_u32_e32 v0, s29, v0
	v_max_i32_e32 v0, 0, v0
	v_lshl_or_b32 v2, v0, 7, v15
	v_lshl_add_u64 v[44:45], s[50:51], 0, v[2:3]
	global_load_lds_dwordx4 v[44:45], off
	s_add_i32 s4, s9, 2
	s_min_u32 s4, s4, 47
	s_lshr_b32 s11, s4, 4
	s_and_b32 s12, s4, 15
	s_lshl_b32 s8, s11, 1
	s_lshl_b32 s13, s64, 4
	s_add_i32 s13, s13, s12
	s_lshr_b32 s14, s12, 2
	s_and_b32 s15, s12, 3
	s_lshl_b32 s16, s64, 2
	s_add_i32 s15, s16, s15
	s_cmp_eq_u32 s11, 1
	s_cselect_b32 s17, s14, 0
	s_cselect_b32 s10, s15, s13
	s_cmp_eq_u32 s11, 2
	s_cselect_b32 s17, s12, s17
	s_cselect_b32 s10, s64, s10
	s_lshl_b32 s5, s10, 7
	v_add_u32_e32 v82, s5, v17
	v_lshlrev_b32_e32 v82, s8, v82
	v_add_u32_e32 v82, s17, v82
	v_lshl_add_u32 v1, v82, 11, v18
	global_load_dwordx4 v[56:59], v1, s[40:41]
	global_load_dwordx4 v[60:63], v1, s[40:41] offset:64
	ds_read_b64_tr_b16 v[84:85], v6 offset:32768
	ds_read_b64_tr_b16 v[88:89], v7 offset:32768
	ds_read_b64_tr_b16 v[92:93], v8 offset:32768
	ds_read_b64_tr_b16 v[96:97], v9 offset:32768
	ds_read_b64_tr_b16 v[86:87], v6 offset:34816
	ds_read_b64_tr_b16 v[90:91], v7 offset:34816
	ds_read_b64_tr_b16 v[94:95], v8 offset:34816
	ds_read_b64_tr_b16 v[98:99], v9 offset:34816
	ds_read_b64_tr_b16 v[100:101], v6 offset:36864
	ds_read_b64_tr_b16 v[104:105], v7 offset:36864
	ds_read_b64_tr_b16 v[108:109], v8 offset:36864
	ds_read_b64_tr_b16 v[112:113], v9 offset:36864
	ds_read_b64_tr_b16 v[102:103], v6 offset:38912
	ds_read_b64_tr_b16 v[106:107], v7 offset:38912
	ds_read_b64_tr_b16 v[110:111], v8 offset:38912
	ds_read_b64_tr_b16 v[114:115], v9 offset:38912
	s_waitcnt lgkmcnt(8)
	v_mfma_f32_16x16x32_bf16 v[228:231], v[84:87], v[172:175], 0
	v_mfma_f32_16x16x32_bf16 v[232:235], v[88:91], v[172:175], 0
	v_mfma_f32_16x16x32_bf16 v[236:239], v[92:95], v[172:175], 0
	v_mfma_f32_16x16x32_bf16 v[240:243], v[96:99], v[172:175], 0
	ds_read_b64_tr_b16 v[84:85], v6 offset:40960
	ds_read_b64_tr_b16 v[88:89], v7 offset:40960
	ds_read_b64_tr_b16 v[92:93], v8 offset:40960
	ds_read_b64_tr_b16 v[96:97], v9 offset:40960
	ds_read_b64_tr_b16 v[86:87], v6 offset:43008
	ds_read_b64_tr_b16 v[90:91], v7 offset:43008
	ds_read_b64_tr_b16 v[94:95], v8 offset:43008
	ds_read_b64_tr_b16 v[98:99], v9 offset:43008
	s_waitcnt lgkmcnt(8)
	v_mfma_f32_16x16x32_bf16 v[228:231], v[100:103], v[176:179], v[228:231]
	v_mfma_f32_16x16x32_bf16 v[232:235], v[104:107], v[176:179], v[232:235]
	v_mfma_f32_16x16x32_bf16 v[236:239], v[108:111], v[176:179], v[236:239]
	v_mfma_f32_16x16x32_bf16 v[240:243], v[112:115], v[176:179], v[240:243]
	ds_read_b64_tr_b16 v[100:101], v6 offset:45056
	ds_read_b64_tr_b16 v[104:105], v7 offset:45056
	ds_read_b64_tr_b16 v[108:109], v8 offset:45056
	ds_read_b64_tr_b16 v[112:113], v9 offset:45056
	ds_read_b64_tr_b16 v[102:103], v6 offset:47104
	ds_read_b64_tr_b16 v[106:107], v7 offset:47104
	ds_read_b64_tr_b16 v[110:111], v8 offset:47104
	ds_read_b64_tr_b16 v[114:115], v9 offset:47104
	s_waitcnt lgkmcnt(8)
	v_mfma_f32_16x16x32_bf16 v[228:231], v[84:87], v[180:183], v[228:231]
	v_mfma_f32_16x16x32_bf16 v[232:235], v[88:91], v[180:183], v[232:235]
	v_mfma_f32_16x16x32_bf16 v[236:239], v[92:95], v[180:183], v[236:239]
	v_mfma_f32_16x16x32_bf16 v[240:243], v[96:99], v[180:183], v[240:243]
	ds_read_b64_tr_b16 v[84:85], v6 offset:49152
	ds_read_b64_tr_b16 v[88:89], v7 offset:49152
	ds_read_b64_tr_b16 v[92:93], v8 offset:49152
	ds_read_b64_tr_b16 v[96:97], v9 offset:49152
	ds_read_b64_tr_b16 v[86:87], v10 offset:32768
	ds_read_b64_tr_b16 v[90:91], v11 offset:32768
	ds_read_b64_tr_b16 v[94:95], v12 offset:32768
	ds_read_b64_tr_b16 v[98:99], v13 offset:32768
	s_waitcnt lgkmcnt(8)
	v_mfma_f32_16x16x32_bf16 v[228:231], v[100:103], v[184:187], v[228:231]
	v_mfma_f32_16x16x32_bf16 v[232:235], v[104:107], v[184:187], v[232:235]
	v_mfma_f32_16x16x32_bf16 v[236:239], v[108:111], v[184:187], v[236:239]
	v_mfma_f32_16x16x32_bf16 v[240:243], v[112:115], v[184:187], v[240:243]
	s_waitcnt lgkmcnt(0)
	v_mfma_f32_16x16x32_bf16 v[228:231], v[84:87], v[188:191], v[228:231]
	v_mfma_f32_16x16x32_bf16 v[232:235], v[88:91], v[188:191], v[232:235]
	v_mfma_f32_16x16x32_bf16 v[236:239], v[92:95], v[188:191], v[236:239]
	v_mfma_f32_16x16x32_bf16 v[240:243], v[96:99], v[188:191], v[240:243]
	v_mov_b32_e32 v0, v36
	v_mov_b32_e32 v1, v36
	s_nop 1
	v_permlane16_swap_b32_e32 v0, v1
	s_nop 1
	v_add_f32_e32 v36, v0, v1
	v_mov_b32_e32 v0, v36
	v_mov_b32_e32 v1, v36
	s_nop 1
	v_permlane32_swap_b32_e32 v0, v1
	s_nop 1
	v_add_f32_e32 v36, v0, v1
	s_cmp_lt_u32 s9, 16
	s_cbranch_scc0 .Latt_hasprev_22
	v_mov_b32_e32 v81, v223
	v_mov_b32_e32 v72, 0
	v_mov_b32_e32 v73, 0
	v_mov_b32_e32 v74, 0
	v_mov_b32_e32 v75, 0
	v_mov_b32_e32 v76, 0
	v_mov_b32_e32 v77, 0
	v_mov_b32_e32 v78, 0
	v_mov_b32_e32 v79, 0
.Latt_hasprev_22:
	v_max_f32_e32 v116, v81, v35
	v_sub_f32_e32 v117, v81, v116
	v_sub_f32_e32 v118, v35, v116
	v_exp_f32_e32 v117, v117
	v_exp_f32_e32 v118, v118
	s_lshl_b32 s5, s24, 7
	v_add_u32_e32 v83, s5, v17
	v_lshlrev_b32_e32 v83, s20, v83
	v_add_u32_e32 v83, s21, v83
	v_fma_f32 v119, v36, v118, v117
	v_rcp_f32_e32 v122, v119
	v_lshl_add_u32 v123, v83, 11, v19
	s_nop 0
	v_mul_f32_e32 v120, v117, v122
	v_mul_f32_e32 v121, v118, v122
	v_lshlrev_b32_e32 v124, 16, v72
	v_and_b32_e32 v125, 0xffff0000, v72
	v_lshlrev_b32_e32 v126, 16, v73
	v_and_b32_e32 v127, 0xffff0000, v73
	v_mul_f32_e32 v124, v120, v124
	v_mul_f32_e32 v125, v120, v125
	v_mul_f32_e32 v126, v120, v126
	v_mul_f32_e32 v127, v120, v127
	v_fma_f32 v124, v228, v121, v124
	v_fma_f32 v125, v229, v121, v125
	v_fma_f32 v126, v230, v121, v126
	v_fma_f32 v127, v231, v121, v127
	v_cvt_pk_bf16_f32 v128, v124, v125
	v_cvt_pk_bf16_f32 v129, v126, v127
	s_nop 0
	global_store_dwordx2 v123, v[128:129], s[42:43] offset:0
	v_lshlrev_b32_e32 v124, 16, v74
	v_and_b32_e32 v125, 0xffff0000, v74
	v_lshlrev_b32_e32 v126, 16, v75
	v_and_b32_e32 v127, 0xffff0000, v75
	v_mul_f32_e32 v124, v120, v124
	v_mul_f32_e32 v125, v120, v125
	v_mul_f32_e32 v126, v120, v126
	v_mul_f32_e32 v127, v120, v127
	v_fma_f32 v124, v232, v121, v124
	v_fma_f32 v125, v233, v121, v125
	v_fma_f32 v126, v234, v121, v126
	v_fma_f32 v127, v235, v121, v127
	v_cvt_pk_bf16_f32 v128, v124, v125
	v_cvt_pk_bf16_f32 v129, v126, v127
	s_nop 0
	global_store_dwordx2 v123, v[128:129], s[42:43] offset:32
	v_lshlrev_b32_e32 v124, 16, v76
	v_and_b32_e32 v125, 0xffff0000, v76
	v_lshlrev_b32_e32 v126, 16, v77
	v_and_b32_e32 v127, 0xffff0000, v77
	v_mul_f32_e32 v124, v120, v124
	v_mul_f32_e32 v125, v120, v125
	v_mul_f32_e32 v126, v120, v126
	v_mul_f32_e32 v127, v120, v127
	v_fma_f32 v124, v236, v121, v124
	v_fma_f32 v125, v237, v121, v125
	v_fma_f32 v126, v238, v121, v126
	v_fma_f32 v127, v239, v121, v127
	v_cvt_pk_bf16_f32 v128, v124, v125
	v_cvt_pk_bf16_f32 v129, v126, v127
	s_nop 0
	global_store_dwordx2 v123, v[128:129], s[42:43] offset:64
	v_lshlrev_b32_e32 v124, 16, v78
	v_and_b32_e32 v125, 0xffff0000, v78
	v_lshlrev_b32_e32 v126, 16, v79
	v_and_b32_e32 v127, 0xffff0000, v79
	v_mul_f32_e32 v124, v120, v124
	v_mul_f32_e32 v125, v120, v125
	v_mul_f32_e32 v126, v120, v126
	v_mul_f32_e32 v127, v120, v127
	v_fma_f32 v124, v240, v121, v124
	v_fma_f32 v125, v241, v121, v125
	v_fma_f32 v126, v242, v121, v126
	v_fma_f32 v127, v243, v121, v127
	v_cvt_pk_bf16_f32 v128, v124, v125
	v_cvt_pk_bf16_f32 v129, v126, v127
	s_nop 0
	global_store_dwordx2 v123, v[128:129], s[42:43] offset:96
	v_log_f32_e32 v130, v119
	v_lshlrev_b32_e32 v131, 2, v83
	s_nop 0
	v_add_f32_e32 v130, v116, v130
	s_mov_b64 exec, 0xffff
	global_store_dword v131, v130, s[44:45]
	s_mov_b64 exec, -1
	v_lshl_add_u32 v1, v82, 11, v19
	global_load_dwordx2 v[72:73], v1, s[42:43] offset:0
	global_load_dwordx2 v[74:75], v1, s[42:43] offset:32
	global_load_dwordx2 v[76:77], v1, s[42:43] offset:64
	global_load_dwordx2 v[78:79], v1, s[42:43] offset:96
	v_lshlrev_b32_e32 v0, 2, v82
	global_load_dword v81, v0, s[44:45]
	s_waitcnt vmcnt(16)
	s_waitcnt lgkmcnt(0)
	s_barrier
	s_add_i32 s53, s53, 2
	s_cmp_lt_u32 s53, 48
	s_cbranch_scc1 .Latt_blk
	s_cmp_eq_u32 s68, 0
	s_cbranch_scc0 .Latt_tail_23
	s_barrier
.Latt_tail_23:
	s_waitcnt vmcnt(0)
	s_add_i32 s63, s63, s86
	s_cmpk_gt_i32 s63, 0xff
	s_barrier
	s_cbranch_scc0 .Latt_unit
